# context-token GQA units dealt to workgroups 8..23 instead of 0..15 (workgroups 0..7 already carry the context NA pairs), on top of v33
# speedup vs baseline: 1.0051x; 1.0051x over previous
.LBB0_625:
	s_setprio 0
	v_readlane_b32 s0, v254, 49
	v_readlane_b32 s1, v254, 50
	s_sub_i32 s4, s80, 8
	s_cmp_lt_u32 s4, 16
	s_cselect_b64 s[2:3], -1, 0
	s_and_b64 s[0:1], s[0:1], s[2:3]
	s_andn2_b64 vcc, exec, s[0:1]
	s_cbranch_vccz .LBB0_630
